# attention chunk loop: wave-uniform loop-exit test done with a scalar compare instead of v_cmp + exec-mask accumulation
# speedup vs baseline: 1.0082x; 1.0069x over previous
.LBB0_475:
	s_or_b64 exec, exec, s[72:73]
	v_add_u32_e32 v188, 31, v188
	s_mov_b32 s3, s79
	s_cmp_eq_u32 s79, s100
	s_cbranch_scc1 .LBB0_455
